# FoX load_q first-pass loads issued together + static prio 1 for waves 4-7 in FoX units too
# baseline (speedup 1.0000x reference)
; DI float shx(float v, int m, int lane) { return __builtin_bit_cast(float, __builtin_amdgcn_ds_bpermute((lane ^ m) << 2, __builtin_bit_cast(int, v))); }
; DI void load_q(bf16x8 (&q)[8], const bf16* qrow, int h, const float* gain, int lane) {
;     float ss = 0.f;
; #pragma unroll
;     for (int s = 0; s < 8; ++s) { const u32x4 raw = *(const u32x4*)(qrow + 16 * s + 8 * h);
; #pragma unroll
;         for (int j = 0; j < 4; ++j) { const float a = __builtin_bit_cast(float, raw[j] << 16), b = __builtin_bit_cast(float, raw[j] & 0xffff0000u); ss += a * a + b * b; } }
;     ss += shx(ss, 32, lane);
; __global__ void __launch_bounds__(NTHR, 2) hybrid_fwd(P p) {
;     ...
;                 if (tid == 0) *qslot = atomicAdd(qctr, 1u);
;                 __syncthreads();
;                 const int v = (int)*qslot;
;                 __syncthreads();
;                 if (v >= 1024) break;
;                 if (v < 512) { const int gg = v < 256 ? 1 : 0, idx = v & 255; if (PH(8)) nsa_unit(p, lds, (idx >> 1) * 4 + ((idx & 1) * 2 + gg), l, wv); }
;                 else { if (PH(7)) fox_unit(p, lds, v - 512, l, wv); }
.LBB0_522:
	s_or_b64 exec, exec, s[2:3]
	v_mov_b32_e32 v0, s29
	s_waitcnt lgkmcnt(0)
	s_barrier
	ds_read_b32 v0, v0
	s_movk_i32 s0, 0x3ff
	s_mov_b64 s[2:3], -1
	s_waitcnt lgkmcnt(0)
	s_barrier
	v_cmp_lt_i32_e32 vcc, s0, v0
	v_readfirstlane_b32 s30, v0
	s_cbranch_vccnz .LBB0_519
	s_cmpk_gt_i32 s30, 0x1ff
	s_cbranch_scc0 .LBB0_588
	s_add_i32 s0, s30, 0xfffffe00
	v_readlane_b32 s1, v252, 5
	v_mbcnt_lo_u32_b32 v114, -1, 0
	v_mbcnt_hi_u32_b32 v114, -1, v114
	s_cmp_ge_u32 s1, 0x100
	s_cbranch_scc0 .Lfox_prio_skip
	s_setprio 1
.Lfox_prio_skip:
	s_lshr_b32 s0, s0, 4
	s_xor_b32 s6, s0, 31
	v_add_u32_e32 v33, s1, v114
	v_ashrrev_i32_e32 v0, 1, v33
	s_lshl_b32 s4, s6, 8
	v_and_b32_e32 v0, 0xffffffe0, v0
	v_and_b32_e32 v115, 31, v114
	s_bfe_u32 s7, s30, 0x10003
	s_and_b32 s0, s30, 7
	v_add_u32_e32 v0, s4, v0
	v_or_b32_e32 v196, v0, v115
	s_lshl_b32 s3, s0, 14
	s_lshl_b32 s1, s7, 13
	s_or_b32 s16, s3, s1
	v_ashrrev_i32_e32 v197, 31, v196
	v_lshl_add_u64 v[2:3], s[16:17], 0, v[196:197]
	v_readlane_b32 s8, v253, 10
	v_bfe_u32 v199, v114, 5, 1
	v_lshlrev_b64 v[2:3], 8, v[2:3]
	v_readlane_b32 s9, v253, 11
	v_lshlrev_b32_e32 v0, 4, v199
	v_and_b32_e32 v208, 63, v114
	v_lshl_add_u64 v[2:3], s[8:9], 0, v[2:3]
	v_lshl_add_u64 v[2:3], v[2:3], 0, v[0:1]
	global_load_dwordx4 v[4:7], v[2:3], off
	global_load_dwordx4 v[136:139], v[2:3], off offset:32
	global_load_dwordx4 v[140:143], v[2:3], off offset:64
	global_load_dwordx4 v[144:147], v[2:3], off offset:96
	global_load_dwordx4 v[148:151], v[2:3], off offset:128
	global_load_dwordx4 v[152:155], v[2:3], off offset:160
	global_load_dwordx4 v[156:159], v[2:3], off offset:192
	global_load_dwordx4 v[160:163], v[2:3], off offset:224
	v_readlane_b32 s8, v255, 9
	v_readlane_b32 s9, v255, 10
	v_lshlrev_b32_e32 v14, 2, v208
	v_xor_b32_e32 v197, 0x80, v14
	s_and_b32 s2, s30, 15
	s_lshl_b32 s14, s2, 15
	v_readlane_b32 s2, v254, 0
	s_add_u32 s2, s2, s14
	v_readlane_b32 s3, v254, 1
	s_mov_b32 s5, s17
	s_addc_u32 s3, s3, 0
	s_mov_b64 s[10:11], 0
	s_waitcnt vmcnt(7)
	v_lshlrev_b32_e32 v8, 16, v4
	v_and_b32_e32 v4, 0xffff0000, v4
	v_mul_f32_e32 v4, v4, v4
	v_fmac_f32_e32 v4, v8, v8
	v_lshlrev_b32_e32 v8, 16, v5
	v_and_b32_e32 v5, 0xffff0000, v5
	v_mul_f32_e32 v5, v5, v5
	v_fmac_f32_e32 v5, v8, v8
	v_add_f32_e32 v4, v4, v5
	v_lshlrev_b32_e32 v5, 16, v6
	v_and_b32_e32 v6, 0xffff0000, v6
	v_mul_f32_e32 v6, v6, v6
	v_fmac_f32_e32 v6, v5, v5
	v_add_f32_e32 v4, v6, v4
	v_and_b32_e32 v6, 0xffff0000, v7
	v_lshlrev_b32_e32 v5, 16, v7
	v_mul_f32_e32 v6, v6, v6
	v_fmac_f32_e32 v6, v5, v5
	v_add_f32_e32 v8, v6, v4
	s_waitcnt vmcnt(6)
	v_mov_b32_e32 v4, v136
	v_mov_b32_e32 v5, v137
	v_mov_b32_e32 v6, v138
	v_mov_b32_e32 v7, v139
	v_lshlrev_b32_e32 v9, 16, v4
	v_and_b32_e32 v4, 0xffff0000, v4
	v_mul_f32_e32 v4, v4, v4
	v_fmac_f32_e32 v4, v9, v9
	v_add_f32_e32 v4, v4, v8
	v_lshlrev_b32_e32 v8, 16, v5
	v_and_b32_e32 v5, 0xffff0000, v5
	v_mul_f32_e32 v5, v5, v5
	v_fmac_f32_e32 v5, v8, v8
	v_add_f32_e32 v4, v5, v4
	v_lshlrev_b32_e32 v5, 16, v6
	v_and_b32_e32 v6, 0xffff0000, v6
	v_mul_f32_e32 v6, v6, v6
	v_fmac_f32_e32 v6, v5, v5
	v_add_f32_e32 v4, v6, v4
	v_and_b32_e32 v6, 0xffff0000, v7
	v_lshlrev_b32_e32 v5, 16, v7
	v_mul_f32_e32 v6, v6, v6
	v_fmac_f32_e32 v6, v5, v5
	v_add_f32_e32 v8, v6, v4
	s_waitcnt vmcnt(5)
	v_mov_b32_e32 v4, v140
	v_mov_b32_e32 v5, v141
	v_mov_b32_e32 v6, v142
	v_mov_b32_e32 v7, v143
	v_lshlrev_b32_e32 v9, 16, v4
	v_and_b32_e32 v4, 0xffff0000, v4
	v_mul_f32_e32 v4, v4, v4
	v_fmac_f32_e32 v4, v9, v9
	v_add_f32_e32 v4, v4, v8
	v_lshlrev_b32_e32 v8, 16, v5
	v_and_b32_e32 v5, 0xffff0000, v5
	v_mul_f32_e32 v5, v5, v5
	v_fmac_f32_e32 v5, v8, v8
	v_add_f32_e32 v4, v5, v4
	v_lshlrev_b32_e32 v5, 16, v6
	v_and_b32_e32 v6, 0xffff0000, v6
	v_mul_f32_e32 v6, v6, v6
	v_fmac_f32_e32 v6, v5, v5
	v_add_f32_e32 v4, v6, v4
	v_and_b32_e32 v6, 0xffff0000, v7
	v_lshlrev_b32_e32 v5, 16, v7
	v_mul_f32_e32 v6, v6, v6
	v_fmac_f32_e32 v6, v5, v5
	v_add_f32_e32 v8, v6, v4
	s_waitcnt vmcnt(4)
	v_mov_b32_e32 v4, v144
	v_mov_b32_e32 v5, v145
	v_mov_b32_e32 v6, v146
	v_mov_b32_e32 v7, v147
	v_lshlrev_b32_e32 v9, 16, v4
	v_and_b32_e32 v4, 0xffff0000, v4
	v_mul_f32_e32 v4, v4, v4
	v_fmac_f32_e32 v4, v9, v9
	v_add_f32_e32 v4, v4, v8
	v_lshlrev_b32_e32 v8, 16, v5
	v_and_b32_e32 v5, 0xffff0000, v5
	v_mul_f32_e32 v5, v5, v5
	v_fmac_f32_e32 v5, v8, v8
	v_add_f32_e32 v4, v5, v4
	v_lshlrev_b32_e32 v5, 16, v6
	v_and_b32_e32 v6, 0xffff0000, v6
	v_mul_f32_e32 v6, v6, v6
	v_fmac_f32_e32 v6, v5, v5
	v_add_f32_e32 v4, v6, v4
	v_and_b32_e32 v6, 0xffff0000, v7
	v_lshlrev_b32_e32 v5, 16, v7
	v_mul_f32_e32 v6, v6, v6
	v_fmac_f32_e32 v6, v5, v5
	v_add_f32_e32 v8, v6, v4
	s_waitcnt vmcnt(3)
	v_mov_b32_e32 v4, v148
	v_mov_b32_e32 v5, v149
	v_mov_b32_e32 v6, v150
	v_mov_b32_e32 v7, v151
	v_lshlrev_b32_e32 v9, 16, v4
	v_and_b32_e32 v4, 0xffff0000, v4
	v_mul_f32_e32 v4, v4, v4
	v_fmac_f32_e32 v4, v9, v9
	v_add_f32_e32 v4, v4, v8
	v_lshlrev_b32_e32 v8, 16, v5
	v_and_b32_e32 v5, 0xffff0000, v5
	v_mul_f32_e32 v5, v5, v5
	v_fmac_f32_e32 v5, v8, v8
	v_add_f32_e32 v4, v5, v4
	v_lshlrev_b32_e32 v5, 16, v6
	v_and_b32_e32 v6, 0xffff0000, v6
	v_mul_f32_e32 v6, v6, v6
	v_fmac_f32_e32 v6, v5, v5
	v_add_f32_e32 v4, v6, v4
	v_and_b32_e32 v6, 0xffff0000, v7
	v_lshlrev_b32_e32 v5, 16, v7
	v_mul_f32_e32 v6, v6, v6
	v_fmac_f32_e32 v6, v5, v5
	v_add_f32_e32 v8, v6, v4
	s_waitcnt vmcnt(2)
; DI void load_q(bf16x8 (&q)[8], const bf16* qrow, int h, const float* gain, int lane) {
;     float ss = 0.f;
; #pragma unroll
;     for (int s = 0; s < 8; ++s) { const u32x4 raw = *(const u32x4*)(qrow + 16 * s + 8 * h);
; #pragma unroll
;         for (int j = 0; j < 4; ++j) { const float a = __builtin_bit_cast(float, raw[j] << 16), b = __builtin_bit_cast(float, raw[j] & 0xffff0000u); ss += a * a + b * b; } }
;     ss += shx(ss, 32, lane);
;     const float rs = rsqrtf(ss * (1.0f / HD) + EPS) * C2;
;     asm volatile("" ::: "memory");
; #pragma unroll
;     for (int s = 0; s < 8; ++s) {
;         const u32x4 raw = *(const u32x4*)(qrow + 16 * s + 8 * h);
;         const f32x4 g0 = *(const f32x4*)(gain + 16 * s + 8 * h), g1 = *(const f32x4*)(gain + 16 * s + 8 * h + 4);
;         u32x4 w;
;         w.x = pk2(__builtin_bit_cast(float, raw.x << 16) * rs * g0[0], __builtin_bit_cast(float, raw.x & 0xffff0000u) * rs * g0[1]);
;         w.y = pk2(__builtin_bit_cast(float, raw.y << 16) * rs * g0[2], __builtin_bit_cast(float, raw.y & 0xffff0000u) * rs * g0[3]);
;         w.z = pk2(__builtin_bit_cast(float, raw.z << 16) * rs * g1[0], __builtin_bit_cast(float, raw.z & 0xffff0000u) * rs * g1[1]);
;         w.w = pk2(__builtin_bit_cast(float, raw.w << 16) * rs * g1[2], __builtin_bit_cast(float, raw.w & 0xffff0000u) * rs * g1[3]);
;         q[s] = __builtin_bit_cast(bf16x8, w);
;     }
; }
; DI void zero_o(f32x16 (&o)[4]) {
; #pragma unroll
;     for (int db = 0; db < 4; ++db)
; #pragma unroll
;         for (int e = 0; e < 16; ++e) o[db][e] = 0.f;
; }
; DI void fox_unit(const P& p, ldsp lds, int u, int l, int wv) {
;     const int tid = tid_of(wv), lane = tid & 63, w = tid >> 6, r32 = lane & 31, h = lane >> 5;
;     const int qb = 31 - (u >> 4), bh = u & 15, b = bh >> 3, hd = bh & 7;
;     const bf16* heads = (const bf16*)(p.ws + WS_HEADS); const bf16* VT = (const bf16*)(p.ws + WS_VT);
;     const int t = qb * 256 + w * 32 + r32;
;     bf16x8 q[8]; load_q(q, heads + ((size_t)hd * M + b * T + t) * HD, h, p.fqn + l * HD, lane);
;     f32x16 o[4]; zero_o(o);
;     AttnCtx c;
;     c.kmat = heads + ((size_t)(8 + hd) * M + b * T) * HD; c.vtm = VT + ((size_t)hd * (M / 64) + b * (T / 64)) * 8192; c.vpitch = 64;
;     c.cumb = (const float*)(p.ws + WS_CUMB) + (size_t)bh * T;
;     int tstart;
;     { const float* fq = p.fqn + l * HD; const float* fk = p.fkn + l * HD;
	v_mov_b32_e32 v4, v152
	v_mov_b32_e32 v5, v153
	v_mov_b32_e32 v6, v154
	v_mov_b32_e32 v7, v155
	v_lshlrev_b32_e32 v9, 16, v4
	v_and_b32_e32 v4, 0xffff0000, v4
	v_mul_f32_e32 v4, v4, v4
	v_fmac_f32_e32 v4, v9, v9
	v_add_f32_e32 v4, v4, v8
	v_lshlrev_b32_e32 v8, 16, v5
	v_and_b32_e32 v5, 0xffff0000, v5
	v_mul_f32_e32 v5, v5, v5
	v_fmac_f32_e32 v5, v8, v8
	v_add_f32_e32 v8, v5, v4
	v_lshlrev_b32_e32 v5, 16, v7
	v_lshlrev_b32_e32 v4, 16, v6
	v_and_b32_e32 v7, 0xffff0000, v7
	v_and_b32_e32 v6, 0xffff0000, v6
	v_pk_mul_f32 v[6:7], v[6:7], v[6:7]
	s_nop 0
	v_pk_fma_f32 v[4:5], v[4:5], v[4:5], v[6:7]
	s_nop 0
	v_add_f32_e32 v4, v4, v8
	v_add_f32_e32 v10, v5, v4
	s_waitcnt vmcnt(1)
	v_mov_b32_e32 v4, v156
	v_mov_b32_e32 v5, v157
	v_mov_b32_e32 v6, v158
	v_mov_b32_e32 v7, v159
	v_lshlrev_b32_e32 v9, 16, v5
	v_lshlrev_b32_e32 v8, 16, v4
	v_and_b32_e32 v5, 0xffff0000, v5
	v_and_b32_e32 v4, 0xffff0000, v4
	v_pk_mul_f32 v[4:5], v[4:5], v[4:5]
	s_nop 0
	v_pk_fma_f32 v[4:5], v[8:9], v[8:9], v[4:5]
	s_nop 0
	v_add_f32_e32 v4, v4, v10
	v_add_f32_e32 v8, v5, v4
	v_lshlrev_b32_e32 v5, 16, v7
	v_lshlrev_b32_e32 v4, 16, v6
	v_and_b32_e32 v7, 0xffff0000, v7
	v_and_b32_e32 v6, 0xffff0000, v6
	v_pk_mul_f32 v[6:7], v[6:7], v[6:7]
	s_nop 0
	v_pk_fma_f32 v[4:5], v[4:5], v[4:5], v[6:7]
	s_nop 0
	v_add_f32_e32 v4, v4, v8
	v_add_f32_e32 v10, v5, v4
	s_waitcnt vmcnt(0)
	v_mov_b32_e32 v4, v160
	v_mov_b32_e32 v5, v161
	v_mov_b32_e32 v6, v162
	v_mov_b32_e32 v7, v163
	global_load_dwordx4 v[136:139], v[2:3], off
	s_waitcnt vmcnt(1)
	v_lshlrev_b32_e32 v9, 16, v5
	v_lshlrev_b32_e32 v8, 16, v4
	v_and_b32_e32 v5, 0xffff0000, v5
	v_and_b32_e32 v4, 0xffff0000, v4
	v_pk_mul_f32 v[4:5], v[4:5], v[4:5]
	s_nop 0
	v_pk_fma_f32 v[4:5], v[8:9], v[8:9], v[4:5]
	s_nop 0
	v_add_f32_e32 v4, v4, v10
	v_add_f32_e32 v8, v5, v4
	v_lshlrev_b32_e32 v5, 16, v7
	v_lshlrev_b32_e32 v4, 16, v6
	v_and_b32_e32 v7, 0xffff0000, v7
	v_and_b32_e32 v6, 0xffff0000, v6
	v_pk_mul_f32 v[6:7], v[6:7], v[6:7]
	v_and_b32_e32 v10, 32, v114
	v_pk_fma_f32 v[4:5], v[4:5], v[4:5], v[6:7]
	s_nop 0
	v_add_f32_e32 v4, v4, v8
	v_add_f32_e32 v201, v5, v4
	global_load_dwordx4 v[180:183], v10, s[8:9] offset:16
	global_load_dwordx4 v[184:187], v10, s[8:9]
	global_load_dwordx4 v[140:143], v[2:3], off offset:32
	global_load_dwordx4 v[172:175], v10, s[8:9] offset:80
	global_load_dwordx4 v[176:179], v10, s[8:9] offset:64
	global_load_dwordx4 v[144:147], v[2:3], off offset:64
	global_load_dwordx4 v[164:167], v10, s[8:9] offset:144
	global_load_dwordx4 v[168:171], v10, s[8:9] offset:128
	global_load_dwordx4 v[148:151], v[2:3], off offset:96
	global_load_dwordx4 v[156:159], v10, s[8:9] offset:208
	global_load_dwordx4 v[160:163], v10, s[8:9] offset:192
	global_load_dwordx4 v[110:113], v[2:3], off offset:128
	global_load_dwordx4 v[106:109], v10, s[8:9] offset:272
	global_load_dwordx4 v[152:155], v10, s[8:9] offset:256
	global_load_dwordx4 v[98:101], v[2:3], off offset:160
	global_load_dwordx4 v[94:97], v10, s[8:9] offset:336
	global_load_dwordx4 v[102:105], v10, s[8:9] offset:320
	global_load_dwordx4 v[86:89], v[2:3], off offset:192
	global_load_dwordx4 v[82:85], v10, s[8:9] offset:400
	global_load_dwordx4 v[90:93], v10, s[8:9] offset:384
	global_load_dwordx4 v[6:9], v[2:3], off offset:224
	s_nop 0
	global_load_dwordx4 v[2:5], v10, s[8:9] offset:464
	s_nop 0
	global_load_dwordx4 v[10:13], v10, s[8:9] offset:448
	s_nop 0
	global_load_dword v15, v14, s[8:9]
	global_load_dword v16, v14, s[8:9] offset:256
	v_readlane_b32 s8, v255, 11
	v_readlane_b32 s9, v255, 12
	ds_bpermute_b32 v210, v197, v201
	s_waitcnt vmcnt(1)
	v_max_f32_e64 v15, |v15|, |v15|
	s_waitcnt vmcnt(0)
	v_max_f32_e64 v16, |v16|, |v16|
	v_max_f32_e32 v15, v15, v16
	global_load_dword v16, v14, s[8:9]
	global_load_dword v17, v14, s[8:9] offset:256
	s_lshl_b64 s[8:9], s[4:5], 2
	s_add_u32 s8, s2, s8
	s_addc_u32 s9, s3, s9
	s_lshl_b32 s5, s6, 2
	s_add_i32 s15, s5, 4
	v_cmp_gt_u32_e32 vcc, s15, v208
	s_waitcnt vmcnt(1)
	v_max_f32_e64 v16, |v16|, |v16|
	s_waitcnt vmcnt(0)
	v_max_f32_e64 v17, |v17|, |v17|
	v_max_f32_e32 v16, v16, v17
	v_xor_b32_e32 v17, 4, v14
	ds_bpermute_b32 v18, v17, v15
	ds_bpermute_b32 v17, v17, v16
	s_waitcnt lgkmcnt(1)
	v_max_f32_e32 v18, v18, v18
	s_waitcnt lgkmcnt(0)
	v_max_f32_e32 v17, v17, v17
	v_max_f32_e32 v15, v15, v18
	v_max_f32_e32 v16, v16, v17
	v_xor_b32_e32 v17, 8, v14
	ds_bpermute_b32 v18, v17, v15
	ds_bpermute_b32 v17, v17, v16
	s_waitcnt lgkmcnt(1)
	v_max_f32_e32 v18, v18, v18
	s_waitcnt lgkmcnt(0)
	v_max_f32_e32 v17, v17, v17
	v_max_f32_e32 v15, v15, v18
	v_max_f32_e32 v16, v16, v17
	v_xor_b32_e32 v17, 16, v14
	ds_bpermute_b32 v18, v17, v15
	ds_bpermute_b32 v17, v17, v16
	s_waitcnt lgkmcnt(1)
	v_max_f32_e32 v18, v18, v18
	s_waitcnt lgkmcnt(0)
	v_max_f32_e32 v17, v17, v17
	v_max_f32_e32 v15, v15, v18
	v_max_f32_e32 v16, v16, v17
	v_xor_b32_e32 v17, 32, v14
	ds_bpermute_b32 v18, v17, v15
	ds_bpermute_b32 v17, v17, v16
	v_xor_b32_e32 v14, 64, v14
	s_waitcnt lgkmcnt(1)
	v_max_f32_e32 v18, v18, v18
	v_max_f32_e32 v15, v15, v18
	s_waitcnt lgkmcnt(0)
	v_max_f32_e32 v17, v17, v17
	v_max_f32_e32 v16, v16, v17
	ds_bpermute_b32 v17, v14, v15
	ds_bpermute_b32 v14, v14, v16
	s_waitcnt lgkmcnt(1)
	v_max_f32_e32 v17, v17, v17
	v_max_f32_e32 v15, v15, v17
	s_waitcnt lgkmcnt(0)
	v_max_f32_e32 v14, v14, v14
	v_max_f32_e32 v14, v16, v14
	ds_bpermute_b32 v16, v197, v15
	s_waitcnt lgkmcnt(0)
	v_max_f32_e32 v16, v16, v16
	v_max_f32_e32 v15, v15, v16
	ds_bpermute_b32 v16, v197, v14
	v_mul_f32_e32 v15, 0x4185307d, v15
	s_waitcnt lgkmcnt(0)
	v_max_f32_e32 v16, v16, v16
	v_max_f32_e32 v14, v14, v16
	v_mul_f32_e32 v190, v14, v15
	global_load_dword v14, v1, s[8:9]
	s_mov_b64 s[8:9], 0
	s_waitcnt vmcnt(0)
	v_fmac_f32_e32 v14, -2.0, v190
	v_add_f32_e32 v14, 0xc2000000, v14
	s_and_saveexec_b64 s[12:13], vcc
	s_cbranch_execz .LBB0_526
	v_lshlrev_b32_e32 v15, 8, v208
	global_load_dword v15, v15, s[2:3] offset:252
	s_waitcnt vmcnt(0)
	v_cmp_lt_f32_e32 vcc, v15, v14
	s_and_b64 s[10:11], vcc, exec
